# cache_convert: 8x-unrolled loads-first fast path (rejoins original loop bottom), on top of v17
# speedup vs baseline: 1.0011x; 1.0011x over previous
; __device__ __forceinline__ void cache_convert(const Params& P, int l, int pct0, int pct1, int part, int nparts) {
;     ...
; #pragma unroll 8
;     for (unsigned gi = g0 + (unsigned)part * 512u + tid; gi < g1; gi += (unsigned)nparts * 512u) {
;         const bool isv = gi >= NGL; const unsigned e = (isv ? gi - NGL : gi) * 8u; const int key = (int)((e >> 9) & 511u);
;         const float* src = (isv ? cv : ck) + e;
;         const f32x4 k0 = *(const f32x4*)src, k1 = *(const f32x4*)(src + 4);
;         *(bf16x8*)((isv ? vb : kb) + e) = pack8v(k0, k1);
;         if (key >= 16) { float* d = (isv ? ov : ok) + e - 16 * 512; *(f32x4*)d = k0; *(f32x4*)(d + 4) = k1; }
.LBB0_679:
	v_readlane_b32 s16, v10, 63
	s_mul_i32 s17, s13, 7
	s_add_u32 s16, s16, s17
	s_cmp_lt_u32 s16, s12
	s_cbranch_scc0 .Lcc_slow
	v_readlane_b32 s22, v253, 61
	v_readlane_b32 s23, v253, 62
	v_readlane_b32 s24, v253, 63
	v_readlane_b32 s25, v254, 0
	s_mov_b64 s[18:19], s[22:23]
	s_mov_b64 s[20:21], s[24:25]
	s_mov_b32 s0, 0xfffff
	s_mov_b32 s16, 0
	s_mov_b32 s17, 0
	v_mov_b32_e32 v85, 0
	v_mov_b32_e32 v87, 0
	v_mov_b32_e32 v89, 0
	v_mov_b32_e32 v91, 0
	v_mov_b32_e32 v93, 0
	v_mov_b32_e32 v95, 0
	v_mov_b32_e32 v97, 0
	v_mov_b32_e32 v99, 0
	v_add_u32_e32 v2, s16, v10
	v_add_u32_e32 v3, s17, v11
	v_cmp_lt_u32_e32 vcc, s0, v2
	v_add_u32_e32 v4, 0xff800000, v3
	v_mov_b32_e32 v5, s19
	v_mov_b32_e32 v6, s21
	v_cndmask_b32_e32 v84, v3, v4, vcc
	v_cndmask_b32_e32 v7, v5, v6, vcc
	v_mov_b32_e32 v5, s18
	v_mov_b32_e32 v8, s20
	v_cndmask_b32_e32 v6, v5, v8, vcc
	v_lshl_add_u64 v[6:7], v[6:7], 0, s[62:63]
	v_lshl_add_u64 v[6:7], v[84:85], 2, v[6:7]
	global_load_dwordx4 v[20:23], v[6:7], off
	global_load_dwordx4 v[24:27], v[6:7], off offset:16
	s_add_u32 s16, s16, s13
	s_add_u32 s17, s17, s14
	v_add_u32_e32 v2, s16, v10
	v_add_u32_e32 v3, s17, v11
	v_cmp_lt_u32_e32 vcc, s0, v2
	v_add_u32_e32 v4, 0xff800000, v3
	v_mov_b32_e32 v5, s19
	v_mov_b32_e32 v6, s21
	v_cndmask_b32_e32 v86, v3, v4, vcc
	v_cndmask_b32_e32 v7, v5, v6, vcc
	v_mov_b32_e32 v5, s18
	v_mov_b32_e32 v8, s20
	v_cndmask_b32_e32 v6, v5, v8, vcc
	v_lshl_add_u64 v[6:7], v[6:7], 0, s[62:63]
	v_lshl_add_u64 v[6:7], v[86:87], 2, v[6:7]
	global_load_dwordx4 v[28:31], v[6:7], off
	global_load_dwordx4 v[32:35], v[6:7], off offset:16
	s_add_u32 s16, s16, s13
	s_add_u32 s17, s17, s14
	v_add_u32_e32 v2, s16, v10
	v_add_u32_e32 v3, s17, v11
	v_cmp_lt_u32_e32 vcc, s0, v2
	v_add_u32_e32 v4, 0xff800000, v3
	v_mov_b32_e32 v5, s19
	v_mov_b32_e32 v6, s21
	v_cndmask_b32_e32 v88, v3, v4, vcc
	v_cndmask_b32_e32 v7, v5, v6, vcc
	v_mov_b32_e32 v5, s18
	v_mov_b32_e32 v8, s20
	v_cndmask_b32_e32 v6, v5, v8, vcc
	v_lshl_add_u64 v[6:7], v[6:7], 0, s[62:63]
	v_lshl_add_u64 v[6:7], v[88:89], 2, v[6:7]
	global_load_dwordx4 v[36:39], v[6:7], off
	global_load_dwordx4 v[40:43], v[6:7], off offset:16
	s_add_u32 s16, s16, s13
	s_add_u32 s17, s17, s14
	v_add_u32_e32 v2, s16, v10
	v_add_u32_e32 v3, s17, v11
	v_cmp_lt_u32_e32 vcc, s0, v2
	v_add_u32_e32 v4, 0xff800000, v3
	v_mov_b32_e32 v5, s19
	v_mov_b32_e32 v6, s21
	v_cndmask_b32_e32 v90, v3, v4, vcc
	v_cndmask_b32_e32 v7, v5, v6, vcc
	v_mov_b32_e32 v5, s18
	v_mov_b32_e32 v8, s20
	v_cndmask_b32_e32 v6, v5, v8, vcc
	v_lshl_add_u64 v[6:7], v[6:7], 0, s[62:63]
	v_lshl_add_u64 v[6:7], v[90:91], 2, v[6:7]
	global_load_dwordx4 v[44:47], v[6:7], off
	global_load_dwordx4 v[48:51], v[6:7], off offset:16
	s_add_u32 s16, s16, s13
	s_add_u32 s17, s17, s14
	v_add_u32_e32 v2, s16, v10
	v_add_u32_e32 v3, s17, v11
	v_cmp_lt_u32_e32 vcc, s0, v2
	v_add_u32_e32 v4, 0xff800000, v3
	v_mov_b32_e32 v5, s19
	v_mov_b32_e32 v6, s21
	v_cndmask_b32_e32 v92, v3, v4, vcc
	v_cndmask_b32_e32 v7, v5, v6, vcc
	v_mov_b32_e32 v5, s18
	v_mov_b32_e32 v8, s20
	v_cndmask_b32_e32 v6, v5, v8, vcc
	v_lshl_add_u64 v[6:7], v[6:7], 0, s[62:63]
	v_lshl_add_u64 v[6:7], v[92:93], 2, v[6:7]
	global_load_dwordx4 v[52:55], v[6:7], off
	global_load_dwordx4 v[56:59], v[6:7], off offset:16
	s_add_u32 s16, s16, s13
	s_add_u32 s17, s17, s14
	v_add_u32_e32 v2, s16, v10
	v_add_u32_e32 v3, s17, v11
	v_cmp_lt_u32_e32 vcc, s0, v2
	v_add_u32_e32 v4, 0xff800000, v3
	v_mov_b32_e32 v5, s19
	v_mov_b32_e32 v6, s21
	v_cndmask_b32_e32 v94, v3, v4, vcc
	v_cndmask_b32_e32 v7, v5, v6, vcc
	v_mov_b32_e32 v5, s18
	v_mov_b32_e32 v8, s20
	v_cndmask_b32_e32 v6, v5, v8, vcc
	v_lshl_add_u64 v[6:7], v[6:7], 0, s[62:63]
	v_lshl_add_u64 v[6:7], v[94:95], 2, v[6:7]
	global_load_dwordx4 v[60:63], v[6:7], off
	global_load_dwordx4 v[64:67], v[6:7], off offset:16
	s_add_u32 s16, s16, s13
	s_add_u32 s17, s17, s14
	v_add_u32_e32 v2, s16, v10
	v_add_u32_e32 v3, s17, v11
	v_cmp_lt_u32_e32 vcc, s0, v2
	v_add_u32_e32 v4, 0xff800000, v3
	v_mov_b32_e32 v5, s19
	v_mov_b32_e32 v6, s21
	v_cndmask_b32_e32 v96, v3, v4, vcc
	v_cndmask_b32_e32 v7, v5, v6, vcc
	v_mov_b32_e32 v5, s18
	v_mov_b32_e32 v8, s20
	v_cndmask_b32_e32 v6, v5, v8, vcc
	v_lshl_add_u64 v[6:7], v[6:7], 0, s[62:63]
	v_lshl_add_u64 v[6:7], v[96:97], 2, v[6:7]
	global_load_dwordx4 v[68:71], v[6:7], off
	global_load_dwordx4 v[72:75], v[6:7], off offset:16
	s_add_u32 s16, s16, s13
	s_add_u32 s17, s17, s14
	v_add_u32_e32 v2, s16, v10
	v_add_u32_e32 v3, s17, v11
	v_cmp_lt_u32_e32 vcc, s0, v2
	v_add_u32_e32 v4, 0xff800000, v3
	v_mov_b32_e32 v5, s19
	v_mov_b32_e32 v6, s21
	v_cndmask_b32_e32 v98, v3, v4, vcc
	v_cndmask_b32_e32 v7, v5, v6, vcc
	v_mov_b32_e32 v5, s18
	v_mov_b32_e32 v8, s20
	v_cndmask_b32_e32 v6, v5, v8, vcc
	v_lshl_add_u64 v[6:7], v[6:7], 0, s[62:63]
	v_lshl_add_u64 v[6:7], v[98:99], 2, v[6:7]
	global_load_dwordx4 v[76:79], v[6:7], off
	global_load_dwordx4 v[80:83], v[6:7], off offset:16
	s_mov_b32 s16, 0
	s_waitcnt vmcnt(0)
	v_add_u32_e32 v2, s16, v10
	s_mov_b32 s0, 0xfffff
	v_mov_b32_e32 v4, 0x24300000
	v_cmp_lt_u32_e32 vcc, s0, v2
	v_mov_b32_e32 v5, 0x28300000
	v_cvt_pk_bf16_f32 v12, v20, v21
	v_cvt_pk_bf16_f32 v13, v22, v23
	v_cndmask_b32_e32 v16, v4, v5, vcc
	v_mov_b32_e32 v17, v1
	v_cvt_pk_bf16_f32 v14, v24, v25
	v_cvt_pk_bf16_f32 v15, v26, v27
	v_lshl_add_u64 v[16:17], s[4:5], 0, v[16:17]
	v_and_b32_e32 v18, 0x3e000, v84
	v_lshl_add_u64 v[16:17], v[84:85], 1, v[16:17]
	v_cmp_ne_u32_e64 s[0:1], 0, v18
	global_store_dwordx4 v[16:17], v[12:15], off
	s_and_saveexec_b64 s[10:11], s[0:1]
	s_cbranch_execz .Lcc_skip0
	v_mov_b32_e32 v4, 0x6222000
	v_mov_b32_e32 v5, 0xe222000
	v_cndmask_b32_e32 v4, v4, v5, vcc
	v_mov_b32_e32 v5, v1
	v_lshl_add_u64 v[4:5], s[6:7], 0, v[4:5]
	v_lshl_add_u64 v[4:5], v[84:85], 2, v[4:5]
	v_add_co_u32_e32 v4, vcc, 0xffff8000, v4
	s_nop 1
	v_addc_co_u32_e32 v5, vcc, -1, v5, vcc
	global_store_dwordx4 v[4:5], v[20:23], off
	global_store_dwordx4 v[4:5], v[24:27], off offset:16
; __device__ __forceinline__ void cache_convert(const Params& P, int l, int pct0, int pct1, int part, int nparts) {
;     ...
;         const bool isv = gi >= NGL; const unsigned e = (isv ? gi - NGL : gi) * 8u; const int key = (int)((e >> 9) & 511u);
;         const float* src = (isv ? cv : ck) + e;
;         const f32x4 k0 = *(const f32x4*)src, k1 = *(const f32x4*)(src + 4);
;         *(bf16x8*)((isv ? vb : kb) + e) = pack8v(k0, k1);
;         if (key >= 16) { float* d = (isv ? ov : ok) + e - 16 * 512; *(f32x4*)d = k0; *(f32x4*)(d + 4) = k1; }
.Lcc_skip0:
	s_or_b64 exec, exec, s[10:11]
	s_add_u32 s16, s16, s13
	v_add_u32_e32 v2, s16, v10
	s_mov_b32 s0, 0xfffff
	v_mov_b32_e32 v4, 0x24300000
	v_cmp_lt_u32_e32 vcc, s0, v2
	v_mov_b32_e32 v5, 0x28300000
	v_cvt_pk_bf16_f32 v100, v28, v29
	v_cvt_pk_bf16_f32 v101, v30, v31
	v_cndmask_b32_e32 v16, v4, v5, vcc
	v_mov_b32_e32 v17, v1
	v_cvt_pk_bf16_f32 v102, v32, v33
	v_cvt_pk_bf16_f32 v103, v34, v35
	v_lshl_add_u64 v[16:17], s[4:5], 0, v[16:17]
	v_and_b32_e32 v18, 0x3e000, v86
	v_lshl_add_u64 v[16:17], v[86:87], 1, v[16:17]
	v_cmp_ne_u32_e64 s[0:1], 0, v18
	global_store_dwordx4 v[16:17], v[100:103], off
	s_and_saveexec_b64 s[10:11], s[0:1]
	s_cbranch_execz .Lcc_skip1
	v_mov_b32_e32 v4, 0x6222000
	v_mov_b32_e32 v5, 0xe222000
	v_cndmask_b32_e32 v4, v4, v5, vcc
	v_mov_b32_e32 v5, v1
	v_lshl_add_u64 v[4:5], s[6:7], 0, v[4:5]
	v_lshl_add_u64 v[4:5], v[86:87], 2, v[4:5]
	v_add_co_u32_e32 v4, vcc, 0xffff8000, v4
	s_nop 1
	v_addc_co_u32_e32 v5, vcc, -1, v5, vcc
	global_store_dwordx4 v[4:5], v[28:31], off
	global_store_dwordx4 v[4:5], v[32:35], off offset:16
.Lcc_skip1:
	s_or_b64 exec, exec, s[10:11]
	s_add_u32 s16, s16, s13
	v_add_u32_e32 v2, s16, v10
	s_mov_b32 s0, 0xfffff
	v_mov_b32_e32 v4, 0x24300000
	v_cmp_lt_u32_e32 vcc, s0, v2
	v_mov_b32_e32 v5, 0x28300000
	v_cvt_pk_bf16_f32 v12, v36, v37
	v_cvt_pk_bf16_f32 v13, v38, v39
	v_cndmask_b32_e32 v16, v4, v5, vcc
	v_mov_b32_e32 v17, v1
	v_cvt_pk_bf16_f32 v14, v40, v41
	v_cvt_pk_bf16_f32 v15, v42, v43
	v_lshl_add_u64 v[16:17], s[4:5], 0, v[16:17]
	v_and_b32_e32 v18, 0x3e000, v88
	v_lshl_add_u64 v[16:17], v[88:89], 1, v[16:17]
	v_cmp_ne_u32_e64 s[0:1], 0, v18
	global_store_dwordx4 v[16:17], v[12:15], off
	s_and_saveexec_b64 s[10:11], s[0:1]
	s_cbranch_execz .Lcc_skip2
	v_mov_b32_e32 v4, 0x6222000
	v_mov_b32_e32 v5, 0xe222000
	v_cndmask_b32_e32 v4, v4, v5, vcc
	v_mov_b32_e32 v5, v1
	v_lshl_add_u64 v[4:5], s[6:7], 0, v[4:5]
	v_lshl_add_u64 v[4:5], v[88:89], 2, v[4:5]
	v_add_co_u32_e32 v4, vcc, 0xffff8000, v4
	s_nop 1
	v_addc_co_u32_e32 v5, vcc, -1, v5, vcc
	global_store_dwordx4 v[4:5], v[36:39], off
	global_store_dwordx4 v[4:5], v[40:43], off offset:16
.Lcc_skip2:
	s_or_b64 exec, exec, s[10:11]
	s_add_u32 s16, s16, s13
	v_add_u32_e32 v2, s16, v10
	s_mov_b32 s0, 0xfffff
	v_mov_b32_e32 v4, 0x24300000
	v_cmp_lt_u32_e32 vcc, s0, v2
	v_mov_b32_e32 v5, 0x28300000
	v_cvt_pk_bf16_f32 v100, v44, v45
	v_cvt_pk_bf16_f32 v101, v46, v47
	v_cndmask_b32_e32 v16, v4, v5, vcc
	v_mov_b32_e32 v17, v1
	v_cvt_pk_bf16_f32 v102, v48, v49
	v_cvt_pk_bf16_f32 v103, v50, v51
	v_lshl_add_u64 v[16:17], s[4:5], 0, v[16:17]
	v_and_b32_e32 v18, 0x3e000, v90
	v_lshl_add_u64 v[16:17], v[90:91], 1, v[16:17]
	v_cmp_ne_u32_e64 s[0:1], 0, v18
	global_store_dwordx4 v[16:17], v[100:103], off
	s_and_saveexec_b64 s[10:11], s[0:1]
	s_cbranch_execz .Lcc_skip3
	v_mov_b32_e32 v4, 0x6222000
	v_mov_b32_e32 v5, 0xe222000
	v_cndmask_b32_e32 v4, v4, v5, vcc
	v_mov_b32_e32 v5, v1
	v_lshl_add_u64 v[4:5], s[6:7], 0, v[4:5]
	v_lshl_add_u64 v[4:5], v[90:91], 2, v[4:5]
	v_add_co_u32_e32 v4, vcc, 0xffff8000, v4
	s_nop 1
	v_addc_co_u32_e32 v5, vcc, -1, v5, vcc
	global_store_dwordx4 v[4:5], v[44:47], off
	global_store_dwordx4 v[4:5], v[48:51], off offset:16
.Lcc_skip3:
	s_or_b64 exec, exec, s[10:11]
	s_add_u32 s16, s16, s13
	v_add_u32_e32 v2, s16, v10
	s_mov_b32 s0, 0xfffff
	v_mov_b32_e32 v4, 0x24300000
	v_cmp_lt_u32_e32 vcc, s0, v2
	v_mov_b32_e32 v5, 0x28300000
	v_cvt_pk_bf16_f32 v12, v52, v53
	v_cvt_pk_bf16_f32 v13, v54, v55
	v_cndmask_b32_e32 v16, v4, v5, vcc
	v_mov_b32_e32 v17, v1
	v_cvt_pk_bf16_f32 v14, v56, v57
	v_cvt_pk_bf16_f32 v15, v58, v59
	v_lshl_add_u64 v[16:17], s[4:5], 0, v[16:17]
	v_and_b32_e32 v18, 0x3e000, v92
	v_lshl_add_u64 v[16:17], v[92:93], 1, v[16:17]
	v_cmp_ne_u32_e64 s[0:1], 0, v18
	global_store_dwordx4 v[16:17], v[12:15], off
	s_and_saveexec_b64 s[10:11], s[0:1]
	s_cbranch_execz .Lcc_skip4
	v_mov_b32_e32 v4, 0x6222000
	v_mov_b32_e32 v5, 0xe222000
	v_cndmask_b32_e32 v4, v4, v5, vcc
	v_mov_b32_e32 v5, v1
	v_lshl_add_u64 v[4:5], s[6:7], 0, v[4:5]
	v_lshl_add_u64 v[4:5], v[92:93], 2, v[4:5]
	v_add_co_u32_e32 v4, vcc, 0xffff8000, v4
	s_nop 1
	v_addc_co_u32_e32 v5, vcc, -1, v5, vcc
	global_store_dwordx4 v[4:5], v[52:55], off
	global_store_dwordx4 v[4:5], v[56:59], off offset:16
; __device__ __forceinline__ void cache_convert(const Params& P, int l, int pct0, int pct1, int part, int nparts) {
;     ...
;     for (unsigned gi = g0 + (unsigned)part * 512u + tid; gi < g1; gi += (unsigned)nparts * 512u) {
;         const bool isv = gi >= NGL; const unsigned e = (isv ? gi - NGL : gi) * 8u; const int key = (int)((e >> 9) & 511u);
;         const float* src = (isv ? cv : ck) + e;
;         const f32x4 k0 = *(const f32x4*)src, k1 = *(const f32x4*)(src + 4);
;         *(bf16x8*)((isv ? vb : kb) + e) = pack8v(k0, k1);
;         if (key >= 16) { float* d = (isv ? ov : ok) + e - 16 * 512; *(f32x4*)d = k0; *(f32x4*)(d + 4) = k1; }
;     }
.Lcc_skip4:
	s_or_b64 exec, exec, s[10:11]
	s_add_u32 s16, s16, s13
	v_add_u32_e32 v2, s16, v10
	s_mov_b32 s0, 0xfffff
	v_mov_b32_e32 v4, 0x24300000
	v_cmp_lt_u32_e32 vcc, s0, v2
	v_mov_b32_e32 v5, 0x28300000
	v_cvt_pk_bf16_f32 v100, v60, v61
	v_cvt_pk_bf16_f32 v101, v62, v63
	v_cndmask_b32_e32 v16, v4, v5, vcc
	v_mov_b32_e32 v17, v1
	v_cvt_pk_bf16_f32 v102, v64, v65
	v_cvt_pk_bf16_f32 v103, v66, v67
	v_lshl_add_u64 v[16:17], s[4:5], 0, v[16:17]
	v_and_b32_e32 v18, 0x3e000, v94
	v_lshl_add_u64 v[16:17], v[94:95], 1, v[16:17]
	v_cmp_ne_u32_e64 s[0:1], 0, v18
	global_store_dwordx4 v[16:17], v[100:103], off
	s_and_saveexec_b64 s[10:11], s[0:1]
	s_cbranch_execz .Lcc_skip5
	v_mov_b32_e32 v4, 0x6222000
	v_mov_b32_e32 v5, 0xe222000
	v_cndmask_b32_e32 v4, v4, v5, vcc
	v_mov_b32_e32 v5, v1
	v_lshl_add_u64 v[4:5], s[6:7], 0, v[4:5]
	v_lshl_add_u64 v[4:5], v[94:95], 2, v[4:5]
	v_add_co_u32_e32 v4, vcc, 0xffff8000, v4
	s_nop 1
	v_addc_co_u32_e32 v5, vcc, -1, v5, vcc
	global_store_dwordx4 v[4:5], v[60:63], off
	global_store_dwordx4 v[4:5], v[64:67], off offset:16
.Lcc_skip5:
	s_or_b64 exec, exec, s[10:11]
	s_add_u32 s16, s16, s13
	v_add_u32_e32 v2, s16, v10
	s_mov_b32 s0, 0xfffff
	v_mov_b32_e32 v4, 0x24300000
	v_cmp_lt_u32_e32 vcc, s0, v2
	v_mov_b32_e32 v5, 0x28300000
	v_cvt_pk_bf16_f32 v12, v68, v69
	v_cvt_pk_bf16_f32 v13, v70, v71
	v_cndmask_b32_e32 v16, v4, v5, vcc
	v_mov_b32_e32 v17, v1
	v_cvt_pk_bf16_f32 v14, v72, v73
	v_cvt_pk_bf16_f32 v15, v74, v75
	v_lshl_add_u64 v[16:17], s[4:5], 0, v[16:17]
	v_and_b32_e32 v18, 0x3e000, v96
	v_lshl_add_u64 v[16:17], v[96:97], 1, v[16:17]
	v_cmp_ne_u32_e64 s[0:1], 0, v18
	global_store_dwordx4 v[16:17], v[12:15], off
	s_and_saveexec_b64 s[10:11], s[0:1]
	s_cbranch_execz .Lcc_skip6
	v_mov_b32_e32 v4, 0x6222000
	v_mov_b32_e32 v5, 0xe222000
	v_cndmask_b32_e32 v4, v4, v5, vcc
	v_mov_b32_e32 v5, v1
	v_lshl_add_u64 v[4:5], s[6:7], 0, v[4:5]
	v_lshl_add_u64 v[4:5], v[96:97], 2, v[4:5]
	v_add_co_u32_e32 v4, vcc, 0xffff8000, v4
	s_nop 1
	v_addc_co_u32_e32 v5, vcc, -1, v5, vcc
	global_store_dwordx4 v[4:5], v[68:71], off
	global_store_dwordx4 v[4:5], v[72:75], off offset:16
.Lcc_skip6:
	s_or_b64 exec, exec, s[10:11]
	s_add_u32 s16, s16, s13
	v_add_u32_e32 v2, s16, v10
	s_mov_b32 s0, 0xfffff
	v_mov_b32_e32 v4, 0x24300000
	v_cmp_lt_u32_e32 vcc, s0, v2
	v_mov_b32_e32 v5, 0x28300000
	v_cvt_pk_bf16_f32 v100, v76, v77
	v_cvt_pk_bf16_f32 v101, v78, v79
	v_cndmask_b32_e32 v16, v4, v5, vcc
	v_mov_b32_e32 v17, v1
	v_cvt_pk_bf16_f32 v102, v80, v81
	v_cvt_pk_bf16_f32 v103, v82, v83
	v_lshl_add_u64 v[16:17], s[4:5], 0, v[16:17]
	v_and_b32_e32 v18, 0x3e000, v98
	v_lshl_add_u64 v[16:17], v[98:99], 1, v[16:17]
	v_cmp_ne_u32_e64 s[0:1], 0, v18
	global_store_dwordx4 v[16:17], v[100:103], off
	s_and_saveexec_b64 s[10:11], s[0:1]
	s_cbranch_execz .Lcc_skip7
	v_mov_b32_e32 v4, 0x6222000
	v_mov_b32_e32 v5, 0xe222000
	v_cndmask_b32_e32 v4, v4, v5, vcc
	v_mov_b32_e32 v5, v1
	v_lshl_add_u64 v[4:5], s[6:7], 0, v[4:5]
	v_lshl_add_u64 v[4:5], v[98:99], 2, v[4:5]
	v_add_co_u32_e32 v4, vcc, 0xffff8000, v4
	s_nop 1
	v_addc_co_u32_e32 v5, vcc, -1, v5, vcc
	global_store_dwordx4 v[4:5], v[76:79], off
	global_store_dwordx4 v[4:5], v[80:83], off offset:16
.Lcc_skip7:
	s_or_b64 exec, exec, s[10:11]
	s_mul_i32 s16, s13, 7
	s_mul_i32 s17, s14, 7
	v_add_u32_e32 v10, s16, v10
	v_add_u32_e32 v11, s17, v11
	s_mov_b64 s[10:11], exec
	s_branch .LBB0_678
